# EpiRes epilogue: 16 residual loads hoisted to loop exit, counted vmcnt instead of vmcnt(0) per load
# baseline (speedup 1.0000x reference)
.LBB0_318:
	s_add_i32 s30, s22, 2
	s_add_u32 s37, s12, 0x80
	s_addc_u32 s23, s13, 0
	s_add_i32 s56, 0, 0x10000
	s_cmp_eq_u32 s5, s22
	s_cselect_b32 s23, s11, s23
	s_cselect_b32 s22, s10, s37
	v_add_u32_e32 v156, s56, v159
	s_cselect_b32 s69, s99, s25
	s_cselect_b32 s68, s98, s24
	s_add_i32 s37, 0, 0x14000
	ds_read_b128 v[152:155], v156
	ds_read_b128 v[178:181], v156 offset:1024
	ds_read_b128 v[182:185], v156 offset:2048
	ds_read_b128 v[186:189], v156 offset:3072
	v_add_u32_e32 v156, s37, v159
	ds_read_b128 v[190:193], v156
	ds_read_b128 v[194:197], v156 offset:1024
	ds_read_b128 v[198:201], v156 offset:2048
	ds_read_b128 v[202:205], v156 offset:3072
	v_lshl_add_u64 v[156:157], s[12:13], 0, v[148:149]
	s_add_i32 m0, s45, 0xc000
	ds_read_b128 v[206:209], v161
	ds_read_b128 v[210:213], v161 offset:1024
	ds_read_b128 v[214:217], v161 offset:2048
	ds_read_b128 v[218:221], v161 offset:3072
	ds_read_b128 v[222:225], v161 offset:4096
	ds_read_b128 v[226:229], v161 offset:5120
	ds_read_b128 v[230:233], v161 offset:6144
	ds_read_b128 v[234:237], v161 offset:7168
	global_load_lds_dwordx4 v[156:157], off
	v_lshl_add_u64 v[156:157], s[12:13], 0, v[150:151]
	s_add_i32 m0, s45, 0xe000
	s_nop 0
	global_load_lds_dwordx4 v[156:157], off
	s_waitcnt vmcnt(8)
	s_waitcnt lgkmcnt(0)
	s_barrier
	s_setprio 1
	s_waitcnt lgkmcnt(0)
	v_mfma_f32_16x16x32_bf16 v[126:129], v[152:155], v[206:209], v[126:129]
	v_mfma_f32_16x16x32_bf16 v[122:125], v[182:185], v[206:209], v[122:125]
	v_mfma_f32_16x16x32_bf16 v[110:113], v[152:155], v[214:217], v[110:113]
	v_mfma_f32_16x16x32_bf16 v[106:109], v[182:185], v[214:217], v[106:109]
	v_mfma_f32_16x16x32_bf16 v[94:97], v[152:155], v[222:225], v[94:97]
	v_mfma_f32_16x16x32_bf16 v[90:93], v[182:185], v[222:225], v[90:93]
	v_mfma_f32_16x16x32_bf16 v[78:81], v[152:155], v[230:233], v[78:81]
	v_mfma_f32_16x16x32_bf16 v[74:77], v[182:185], v[230:233], v[74:77]
	v_mfma_f32_16x16x32_bf16 v[126:129], v[178:181], v[210:213], v[126:129]
	v_mfma_f32_16x16x32_bf16 v[122:125], v[186:189], v[210:213], v[122:125]
	v_mfma_f32_16x16x32_bf16 v[110:113], v[178:181], v[218:221], v[110:113]
	v_mfma_f32_16x16x32_bf16 v[106:109], v[186:189], v[218:221], v[106:109]
	v_mfma_f32_16x16x32_bf16 v[94:97], v[178:181], v[226:229], v[94:97]
	v_mfma_f32_16x16x32_bf16 v[90:93], v[186:189], v[226:229], v[90:93]
	v_mfma_f32_16x16x32_bf16 v[78:81], v[178:181], v[234:237], v[78:81]
	v_mfma_f32_16x16x32_bf16 v[74:77], v[186:189], v[234:237], v[74:77]
	s_setprio 0
	s_setprio 1
	v_mfma_f32_16x16x32_bf16 v[118:121], v[190:193], v[206:209], v[118:121]
	v_mfma_f32_16x16x32_bf16 v[114:117], v[198:201], v[206:209], v[114:117]
	v_mfma_f32_16x16x32_bf16 v[102:105], v[190:193], v[214:217], v[102:105]
	v_mfma_f32_16x16x32_bf16 v[98:101], v[198:201], v[214:217], v[98:101]
	v_mfma_f32_16x16x32_bf16 v[86:89], v[190:193], v[222:225], v[86:89]
	v_mfma_f32_16x16x32_bf16 v[82:85], v[198:201], v[222:225], v[82:85]
	v_mfma_f32_16x16x32_bf16 v[70:73], v[190:193], v[230:233], v[70:73]
	v_mfma_f32_16x16x32_bf16 v[66:69], v[198:201], v[230:233], v[66:69]
	v_mfma_f32_16x16x32_bf16 v[118:121], v[194:197], v[210:213], v[118:121]
	v_mfma_f32_16x16x32_bf16 v[114:117], v[202:205], v[210:213], v[114:117]
	v_mfma_f32_16x16x32_bf16 v[102:105], v[194:197], v[218:221], v[102:105]
	v_mfma_f32_16x16x32_bf16 v[98:101], v[202:205], v[218:221], v[98:101]
	s_setprio 2
	s_barrier
	v_mfma_f32_16x16x32_bf16 v[86:89], v[194:197], v[226:229], v[86:89]
	v_mfma_f32_16x16x32_bf16 v[82:85], v[202:205], v[226:229], v[82:85]
	v_mfma_f32_16x16x32_bf16 v[70:73], v[194:197], v[234:237], v[70:73]
	v_mfma_f32_16x16x32_bf16 v[66:69], v[202:205], v[234:237], v[66:69]
	s_setprio 0
	s_add_i32 s56, s56, s26
	v_lshl_add_u64 v[156:157], s[68:69], 0, v[134:135]
	s_mov_b32 m0, s56
	ds_read_b128 v[206:209], v161 offset:16384
	ds_read_b128 v[210:213], v161 offset:17408
	ds_read_b128 v[214:217], v161 offset:18432
	ds_read_b128 v[218:221], v161 offset:19456
	ds_read_b128 v[222:225], v161 offset:20480
	ds_read_b128 v[226:229], v161 offset:21504
	ds_read_b128 v[230:233], v161 offset:22528
	ds_read_b128 v[234:237], v161 offset:23552
	global_load_lds_dwordx4 v[156:157], off
	s_add_i32 m0, s56, 0x2000
	v_lshl_add_u64 v[164:165], s[68:69], 0, v[132:133]
	s_add_u32 s68, s68, s92
	s_addc_u32 s69, s69, 0
	s_add_i32 s37, s37, s26
	global_load_lds_dwordx4 v[164:165], off
	v_lshl_add_u64 v[238:239], s[68:69], 0, v[134:135]
	s_mov_b32 m0, s37
	v_lshl_add_u64 v[240:241], s[68:69], 0, v[132:133]
	global_load_lds_dwordx4 v[238:239], off
	s_add_i32 m0, s37, 0x2000
	v_lshl_add_u64 v[242:243], s[22:23], 0, v[146:147]
	global_load_lds_dwordx4 v[240:241], off
	s_mov_b32 m0, s45
	v_lshl_add_u64 v[244:245], s[22:23], 0, v[144:145]
	global_load_lds_dwordx4 v[242:243], off
	s_mov_b32 m0, s46
	s_nop 0
	global_load_lds_dwordx4 v[244:245], off
	s_waitcnt vmcnt(8)
	s_waitcnt lgkmcnt(0)
	s_barrier
	s_setprio 1
	s_waitcnt lgkmcnt(0)
	v_mfma_f32_16x16x32_bf16 v[62:65], v[152:155], v[206:209], v[62:65]
	v_mfma_f32_16x16x32_bf16 v[58:61], v[182:185], v[206:209], v[58:61]
	v_mfma_f32_16x16x32_bf16 v[46:49], v[152:155], v[214:217], v[46:49]
	v_mfma_f32_16x16x32_bf16 v[42:45], v[182:185], v[214:217], v[42:45]
	v_mfma_f32_16x16x32_bf16 v[30:33], v[152:155], v[222:225], v[30:33]
	v_mfma_f32_16x16x32_bf16 v[26:29], v[182:185], v[222:225], v[26:29]
	v_mfma_f32_16x16x32_bf16 v[14:17], v[152:155], v[230:233], v[14:17]
	v_mfma_f32_16x16x32_bf16 v[10:13], v[182:185], v[230:233], v[10:13]
	v_mfma_f32_16x16x32_bf16 v[62:65], v[178:181], v[210:213], v[62:65]
	v_mfma_f32_16x16x32_bf16 v[58:61], v[186:189], v[210:213], v[58:61]
	v_mfma_f32_16x16x32_bf16 v[46:49], v[178:181], v[218:221], v[46:49]
	v_mfma_f32_16x16x32_bf16 v[42:45], v[186:189], v[218:221], v[42:45]
	v_mfma_f32_16x16x32_bf16 v[30:33], v[178:181], v[226:229], v[30:33]
	v_mfma_f32_16x16x32_bf16 v[26:29], v[186:189], v[226:229], v[26:29]
	v_mfma_f32_16x16x32_bf16 v[14:17], v[178:181], v[234:237], v[14:17]
	v_mfma_f32_16x16x32_bf16 v[10:13], v[186:189], v[234:237], v[10:13]
	s_setprio 0
	s_setprio 1
	v_mfma_f32_16x16x32_bf16 v[54:57], v[190:193], v[206:209], v[54:57]
	v_mfma_f32_16x16x32_bf16 v[50:53], v[198:201], v[206:209], v[50:53]
	v_mfma_f32_16x16x32_bf16 v[38:41], v[190:193], v[214:217], v[38:41]
	v_mfma_f32_16x16x32_bf16 v[34:37], v[198:201], v[214:217], v[34:37]
	v_mfma_f32_16x16x32_bf16 v[22:25], v[190:193], v[222:225], v[22:25]
	v_mfma_f32_16x16x32_bf16 v[18:21], v[198:201], v[222:225], v[18:21]
	v_mfma_f32_16x16x32_bf16 v[6:9], v[190:193], v[230:233], v[6:9]
	v_mfma_f32_16x16x32_bf16 v[2:5], v[198:201], v[230:233], v[2:5]
	v_mfma_f32_16x16x32_bf16 v[54:57], v[194:197], v[210:213], v[54:57]
	v_mfma_f32_16x16x32_bf16 v[50:53], v[202:205], v[210:213], v[50:53]
	v_mfma_f32_16x16x32_bf16 v[38:41], v[194:197], v[218:221], v[38:41]
	v_mfma_f32_16x16x32_bf16 v[34:37], v[202:205], v[218:221], v[34:37]
	s_setprio 2
	s_barrier
	v_mfma_f32_16x16x32_bf16 v[22:25], v[194:197], v[226:229], v[22:25]
	v_mfma_f32_16x16x32_bf16 v[18:21], v[202:205], v[226:229], v[18:21]
	v_mfma_f32_16x16x32_bf16 v[6:9], v[194:197], v[234:237], v[6:9]
	v_mfma_f32_16x16x32_bf16 v[2:5], v[202:205], v[234:237], v[2:5]
	s_setprio 0
	s_add_i32 s37, 0, 0x18000
	v_add_u32_e32 v162, s37, v159
	s_add_i32 s56, 0, 0x1c000
	ds_read_b128 v[152:155], v162
	ds_read_b128 v[178:181], v162 offset:1024
	ds_read_b128 v[182:185], v162 offset:2048
	ds_read_b128 v[186:189], v162 offset:3072
	v_add_u32_e32 v162, s56, v159
	ds_read_b128 v[190:193], v162
	ds_read_b128 v[194:197], v162 offset:1024
	ds_read_b128 v[198:201], v162 offset:2048
	ds_read_b128 v[202:205], v162 offset:3072
	s_add_u32 s22, s22, s92
	s_addc_u32 s23, s23, 0
	s_mov_b32 m0, s47
	v_lshl_add_u64 v[246:247], s[22:23], 0, v[146:147]
	ds_read_b128 v[206:209], v161 offset:32768
	ds_read_b128 v[210:213], v161 offset:33792
	ds_read_b128 v[214:217], v161 offset:34816
	ds_read_b128 v[218:221], v161 offset:35840
	ds_read_b128 v[222:225], v161 offset:36864
	ds_read_b128 v[226:229], v161 offset:37888
	ds_read_b128 v[230:233], v161 offset:38912
	ds_read_b128 v[234:237], v161 offset:39936
	global_load_lds_dwordx4 v[246:247], off
	v_lshl_add_u64 v[246:247], s[22:23], 0, v[144:145]
	s_mov_b32 m0, s50
	s_nop 0
	global_load_lds_dwordx4 v[246:247], off
	s_waitcnt vmcnt(8)
	s_waitcnt lgkmcnt(0)
	s_barrier
	s_setprio 1
	s_waitcnt lgkmcnt(0)
	v_mfma_f32_16x16x32_bf16 v[126:129], v[152:155], v[206:209], v[126:129]
	v_mfma_f32_16x16x32_bf16 v[122:125], v[182:185], v[206:209], v[122:125]
	v_mfma_f32_16x16x32_bf16 v[110:113], v[152:155], v[214:217], v[110:113]
	v_mfma_f32_16x16x32_bf16 v[106:109], v[182:185], v[214:217], v[106:109]
	v_mfma_f32_16x16x32_bf16 v[94:97], v[152:155], v[222:225], v[94:97]
	v_mfma_f32_16x16x32_bf16 v[90:93], v[182:185], v[222:225], v[90:93]
	v_mfma_f32_16x16x32_bf16 v[78:81], v[152:155], v[230:233], v[78:81]
	v_mfma_f32_16x16x32_bf16 v[74:77], v[182:185], v[230:233], v[74:77]
	v_mfma_f32_16x16x32_bf16 v[126:129], v[178:181], v[210:213], v[126:129]
	v_mfma_f32_16x16x32_bf16 v[122:125], v[186:189], v[210:213], v[122:125]
	v_mfma_f32_16x16x32_bf16 v[110:113], v[178:181], v[218:221], v[110:113]
	v_mfma_f32_16x16x32_bf16 v[106:109], v[186:189], v[218:221], v[106:109]
	v_mfma_f32_16x16x32_bf16 v[94:97], v[178:181], v[226:229], v[94:97]
	v_mfma_f32_16x16x32_bf16 v[90:93], v[186:189], v[226:229], v[90:93]
	v_mfma_f32_16x16x32_bf16 v[78:81], v[178:181], v[234:237], v[78:81]
	v_mfma_f32_16x16x32_bf16 v[74:77], v[186:189], v[234:237], v[74:77]
	s_setprio 0
	s_setprio 1
	v_mfma_f32_16x16x32_bf16 v[118:121], v[190:193], v[206:209], v[118:121]
	v_mfma_f32_16x16x32_bf16 v[114:117], v[198:201], v[206:209], v[114:117]
	v_mfma_f32_16x16x32_bf16 v[102:105], v[190:193], v[214:217], v[102:105]
	v_mfma_f32_16x16x32_bf16 v[98:101], v[198:201], v[214:217], v[98:101]
	v_mfma_f32_16x16x32_bf16 v[86:89], v[190:193], v[222:225], v[86:89]
	v_mfma_f32_16x16x32_bf16 v[82:85], v[198:201], v[222:225], v[82:85]
	v_mfma_f32_16x16x32_bf16 v[70:73], v[190:193], v[230:233], v[70:73]
	v_mfma_f32_16x16x32_bf16 v[66:69], v[198:201], v[230:233], v[66:69]
	v_mfma_f32_16x16x32_bf16 v[118:121], v[194:197], v[210:213], v[118:121]
	v_mfma_f32_16x16x32_bf16 v[114:117], v[202:205], v[210:213], v[114:117]
	v_mfma_f32_16x16x32_bf16 v[102:105], v[194:197], v[218:221], v[102:105]
	v_mfma_f32_16x16x32_bf16 v[98:101], v[202:205], v[218:221], v[98:101]
	s_setprio 2
	s_barrier
	v_mfma_f32_16x16x32_bf16 v[86:89], v[194:197], v[226:229], v[86:89]
	v_mfma_f32_16x16x32_bf16 v[82:85], v[202:205], v[226:229], v[82:85]
	v_mfma_f32_16x16x32_bf16 v[70:73], v[194:197], v[234:237], v[70:73]
	v_mfma_f32_16x16x32_bf16 v[66:69], v[202:205], v[234:237], v[66:69]
	s_setprio 0
	s_add_i32 s22, s37, s26
	v_lshl_add_u64 v[156:157], v[156:157], 0, s[66:67]
	s_mov_b32 m0, s22
	ds_read_b128 v[206:209], v161 offset:49152
	ds_read_b128 v[210:213], v161 offset:50176
	ds_read_b128 v[214:217], v161 offset:51200
	ds_read_b128 v[218:221], v161 offset:52224
	ds_read_b128 v[222:225], v161 offset:53248
	ds_read_b128 v[226:229], v161 offset:54272
	ds_read_b128 v[230:233], v161 offset:55296
	ds_read_b128 v[234:237], v161 offset:56320
	global_load_lds_dwordx4 v[156:157], off
	v_lshl_add_u64 v[156:157], v[164:165], 0, s[66:67]
	s_add_i32 m0, s22, 0x2000
	s_add_i32 s22, s56, s26
	global_load_lds_dwordx4 v[156:157], off
	v_lshl_add_u64 v[156:157], v[238:239], 0, s[66:67]
	s_mov_b32 m0, s22
	s_nop 0
	global_load_lds_dwordx4 v[156:157], off
	v_lshl_add_u64 v[156:157], v[240:241], 0, s[66:67]
	s_add_i32 m0, s22, 0x2000
	s_nop 0
	global_load_lds_dwordx4 v[156:157], off
	v_lshl_add_u64 v[156:157], v[242:243], 0, s[66:67]
	s_mov_b32 m0, s51
	s_nop 0
	global_load_lds_dwordx4 v[156:157], off
	v_lshl_add_u64 v[156:157], v[244:245], 0, s[66:67]
	s_mov_b32 m0, s52
	s_nop 0
	global_load_lds_dwordx4 v[156:157], off
	s_waitcnt vmcnt(8)
	s_waitcnt lgkmcnt(0)
	s_barrier
	s_setprio 1
	s_waitcnt lgkmcnt(0)
	v_mfma_f32_16x16x32_bf16 v[62:65], v[152:155], v[206:209], v[62:65]
	v_mfma_f32_16x16x32_bf16 v[58:61], v[182:185], v[206:209], v[58:61]
	v_mfma_f32_16x16x32_bf16 v[46:49], v[152:155], v[214:217], v[46:49]
	v_mfma_f32_16x16x32_bf16 v[42:45], v[182:185], v[214:217], v[42:45]
	v_mfma_f32_16x16x32_bf16 v[30:33], v[152:155], v[222:225], v[30:33]
	v_mfma_f32_16x16x32_bf16 v[26:29], v[182:185], v[222:225], v[26:29]
	v_mfma_f32_16x16x32_bf16 v[14:17], v[152:155], v[230:233], v[14:17]
	v_mfma_f32_16x16x32_bf16 v[10:13], v[182:185], v[230:233], v[10:13]
	v_mfma_f32_16x16x32_bf16 v[62:65], v[178:181], v[210:213], v[62:65]
	v_mfma_f32_16x16x32_bf16 v[58:61], v[186:189], v[210:213], v[58:61]
	v_mfma_f32_16x16x32_bf16 v[46:49], v[178:181], v[218:221], v[46:49]
	v_mfma_f32_16x16x32_bf16 v[42:45], v[186:189], v[218:221], v[42:45]
	v_mfma_f32_16x16x32_bf16 v[30:33], v[178:181], v[226:229], v[30:33]
	v_mfma_f32_16x16x32_bf16 v[26:29], v[186:189], v[226:229], v[26:29]
	v_mfma_f32_16x16x32_bf16 v[14:17], v[178:181], v[234:237], v[14:17]
	v_mfma_f32_16x16x32_bf16 v[10:13], v[186:189], v[234:237], v[10:13]
	s_setprio 0
	s_setprio 1
	v_mfma_f32_16x16x32_bf16 v[54:57], v[190:193], v[206:209], v[54:57]
	v_mfma_f32_16x16x32_bf16 v[50:53], v[198:201], v[206:209], v[50:53]
	v_mfma_f32_16x16x32_bf16 v[38:41], v[190:193], v[214:217], v[38:41]
	v_mfma_f32_16x16x32_bf16 v[34:37], v[198:201], v[214:217], v[34:37]
	v_mfma_f32_16x16x32_bf16 v[22:25], v[190:193], v[222:225], v[22:25]
	v_mfma_f32_16x16x32_bf16 v[18:21], v[198:201], v[222:225], v[18:21]
	v_mfma_f32_16x16x32_bf16 v[6:9], v[190:193], v[230:233], v[6:9]
	v_mfma_f32_16x16x32_bf16 v[2:5], v[198:201], v[230:233], v[2:5]
	v_mfma_f32_16x16x32_bf16 v[54:57], v[194:197], v[210:213], v[54:57]
	v_mfma_f32_16x16x32_bf16 v[50:53], v[202:205], v[210:213], v[50:53]
	v_mfma_f32_16x16x32_bf16 v[38:41], v[194:197], v[218:221], v[38:41]
	v_mfma_f32_16x16x32_bf16 v[34:37], v[202:205], v[218:221], v[34:37]
	s_setprio 2
	s_barrier
	v_mfma_f32_16x16x32_bf16 v[22:25], v[194:197], v[226:229], v[22:25]
	v_mfma_f32_16x16x32_bf16 v[18:21], v[202:205], v[226:229], v[18:21]
	v_mfma_f32_16x16x32_bf16 v[6:9], v[194:197], v[234:237], v[6:9]
	v_mfma_f32_16x16x32_bf16 v[2:5], v[202:205], v[234:237], v[2:5]
	s_setprio 0
	s_add_u32 s12, s12, 0x100
	s_addc_u32 s13, s13, 0
	s_add_u32 s24, s24, 0x100
	s_addc_u32 s25, s25, 0
	s_cmp_ge_u32 s30, s4
	s_mov_b32 s22, s30
	s_cbranch_scc0 .LBB0_318
	v_lshl_or_b32 v252, s19, 8, v160
	v_ashrrev_i32_e32 v253, 31, v252
	v_lshl_add_u32 v250, s21, 8, v131
	v_ashrrev_i32_e32 v251, 31, v250
	v_lshlrev_b64 v[250:251], 11, v[250:251]
	v_lshl_add_u64 v[250:251], s[78:79], 0, v[250:251]
	v_lshl_add_u64 v[250:251], v[252:253], 1, v[250:251]
	global_load_dwordx4 v[186:189], v[250:251], off
	global_load_dwordx4 v[190:193], v[250:251], off offset:256
	v_lshl_add_u32 v250, s21, 8, v131
	v_add_u32_e32 v250, 16, v250
	v_ashrrev_i32_e32 v251, 31, v250
	v_lshlrev_b64 v[250:251], 11, v[250:251]
	v_lshl_add_u64 v[250:251], s[78:79], 0, v[250:251]
	v_lshl_add_u64 v[250:251], v[252:253], 1, v[250:251]
	global_load_dwordx4 v[194:197], v[250:251], off
	global_load_dwordx4 v[198:201], v[250:251], off offset:256
	v_lshl_add_u32 v250, s21, 8, v131
	v_add_u32_e32 v250, 32, v250
	v_ashrrev_i32_e32 v251, 31, v250
	v_lshlrev_b64 v[250:251], 11, v[250:251]
	v_lshl_add_u64 v[250:251], s[78:79], 0, v[250:251]
	v_lshl_add_u64 v[250:251], v[252:253], 1, v[250:251]
	global_load_dwordx4 v[202:205], v[250:251], off
	global_load_dwordx4 v[206:209], v[250:251], off offset:256
	v_lshl_add_u32 v250, s21, 8, v131
	v_add_u32_e32 v250, 48, v250
	v_ashrrev_i32_e32 v251, 31, v250
	v_lshlrev_b64 v[250:251], 11, v[250:251]
	v_lshl_add_u64 v[250:251], s[78:79], 0, v[250:251]
	v_lshl_add_u64 v[250:251], v[252:253], 1, v[250:251]
	global_load_dwordx4 v[210:213], v[250:251], off
	global_load_dwordx4 v[214:217], v[250:251], off offset:256
	v_lshl_add_u32 v250, s21, 8, v131
	v_add_u32_e32 v250, 0x80, v250
	v_ashrrev_i32_e32 v251, 31, v250
	v_lshlrev_b64 v[250:251], 11, v[250:251]
	v_lshl_add_u64 v[250:251], s[78:79], 0, v[250:251]
	v_lshl_add_u64 v[250:251], v[252:253], 1, v[250:251]
	global_load_dwordx4 v[218:221], v[250:251], off
	global_load_dwordx4 v[222:225], v[250:251], off offset:256
	v_lshl_add_u32 v250, s21, 8, v131
	v_add_u32_e32 v250, 0x90, v250
	v_ashrrev_i32_e32 v251, 31, v250
	v_lshlrev_b64 v[250:251], 11, v[250:251]
	v_lshl_add_u64 v[250:251], s[78:79], 0, v[250:251]
	v_lshl_add_u64 v[250:251], v[252:253], 1, v[250:251]
	global_load_dwordx4 v[226:229], v[250:251], off
	global_load_dwordx4 v[230:233], v[250:251], off offset:256
	v_lshl_add_u32 v250, s21, 8, v131
	v_add_u32_e32 v250, 0xa0, v250
	v_ashrrev_i32_e32 v251, 31, v250
	v_lshlrev_b64 v[250:251], 11, v[250:251]
	v_lshl_add_u64 v[250:251], s[78:79], 0, v[250:251]
	v_lshl_add_u64 v[250:251], v[252:253], 1, v[250:251]
	global_load_dwordx4 v[234:237], v[250:251], off
	global_load_dwordx4 v[238:241], v[250:251], off offset:256
	v_lshl_add_u32 v250, s21, 8, v131
	v_add_u32_e32 v250, 0xb0, v250
	v_ashrrev_i32_e32 v251, 31, v250
	v_lshlrev_b64 v[250:251], 11, v[250:251]
	v_lshl_add_u64 v[250:251], s[78:79], 0, v[250:251]
	v_lshl_add_u64 v[250:251], v[252:253], 1, v[250:251]
	global_load_dwordx4 v[242:245], v[250:251], off
	global_load_dwordx4 v[246:249], v[250:251], off offset:256
	s_and_b64 vcc, exec, s[96:97]
	s_cbranch_vccz .LBB0_321
	s_barrier
.LBB0_321:
	v_cmp_lt_i32_e32 vcc, v176, v171
	v_lshl_add_u32 v154, s21, 8, v131
	v_lshl_or_b32 v152, s19, 8, v160
	v_cndmask_b32_e32 v155, v170, v176, vcc
	v_cmp_lt_i32_e32 vcc, v177, v171
	v_lshlrev_b32_e32 v164, 2, v155
	v_ashrrev_i32_e32 v153, 31, v152
	v_cndmask_b32_e32 v155, v170, v177, vcc
	v_lshlrev_b32_e32 v162, 2, v155
	v_ashrrev_i32_e32 v155, 31, v154
	v_lshlrev_b64 v[156:157], 11, v[154:155]
	v_lshl_add_u64 v[156:157], s[78:79], 0, v[156:157]
	v_lshl_add_u64 v[156:157], v[152:153], 1, v[156:157]
	s_lshl_b32 vcc_lo, s19, 2
	s_ashr_i32 vcc_hi, vcc_lo, 31
	s_waitcnt vmcnt(15)
	v_lshlrev_b32_e32 v182, 16, v186
	v_and_b32_e32 v183, 0xffff0000, v186
	v_lshlrev_b32_e32 v178, 16, v187
	v_and_b32_e32 v179, 0xffff0000, v187
	v_lshlrev_b32_e32 v184, 16, v188
	v_and_b32_e32 v185, 0xffff0000, v188
	v_lshlrev_b32_e32 v180, 16, v189
	v_and_b32_e32 v181, 0xffff0000, v189
	v_pk_add_f32 v[128:129], v[128:129], v[178:179]
	v_pk_add_f32 v[126:127], v[126:127], v[182:183]
	v_pk_add_f32 v[178:179], v[124:125], v[180:181]
	v_pk_add_f32 v[180:181], v[122:123], v[184:185]
	v_cvt_pk_bf16_f32 v122, v126, v127
	v_cvt_pk_bf16_f32 v123, v128, v129
	v_cvt_pk_bf16_f32 v124, v180, v181
	v_cvt_pk_bf16_f32 v125, v178, v179
	global_store_dwordx4 v[156:157], v[122:125], off
	s_nop 1
	v_mul_f32_e32 v122, v127, v127
	v_mul_f32_e32 v123, v129, v129
	v_fmac_f32_e32 v122, v126, v126
	v_fmac_f32_e32 v123, v128, v128
	v_add_f32_e32 v122, v122, v123
	v_mul_f32_e32 v123, v181, v181
	v_fmac_f32_e32 v123, v180, v180
	v_add_f32_e32 v122, v123, v122
	v_mul_f32_e32 v123, v179, v179
	v_fmac_f32_e32 v123, v178, v178
	v_add_f32_e32 v165, v123, v122
	s_waitcnt vmcnt(15)
	v_lshlrev_b32_e32 v126, 16, v190
	v_and_b32_e32 v127, 0xffff0000, v190
	v_lshlrev_b32_e32 v122, 16, v191
	v_and_b32_e32 v123, 0xffff0000, v191
	v_lshlrev_b32_e32 v128, 16, v192
	v_and_b32_e32 v129, 0xffff0000, v192
	v_lshlrev_b32_e32 v124, 16, v193
	v_and_b32_e32 v125, 0xffff0000, v193
	v_pk_add_f32 v[120:121], v[120:121], v[122:123]
	v_pk_add_f32 v[118:119], v[118:119], v[126:127]
	v_pk_add_f32 v[122:123], v[116:117], v[124:125]
	v_pk_add_f32 v[124:125], v[114:115], v[128:129]
	v_cvt_pk_bf16_f32 v114, v118, v119
	v_cvt_pk_bf16_f32 v115, v120, v121
	v_cvt_pk_bf16_f32 v116, v124, v125
	v_cvt_pk_bf16_f32 v117, v122, v123
	global_store_dwordx4 v[156:157], v[114:117], off offset:256
	s_nop 1
	v_mul_f32_e32 v114, v119, v119
	v_mul_f32_e32 v115, v121, v121
	v_fmac_f32_e32 v114, v118, v118
	v_fmac_f32_e32 v115, v120, v120
	v_add_f32_e32 v114, v114, v115
	v_mul_f32_e32 v115, v125, v125
	v_fmac_f32_e32 v115, v124, v124
	v_add_f32_e32 v114, v115, v114
	v_mul_f32_e32 v115, v123, v123
	v_fmac_f32_e32 v115, v122, v122
	v_add_f32_e32 v114, v115, v114
	v_add_f32_e32 v114, v165, v114
	ds_bpermute_b32 v115, v164, v114
	s_waitcnt lgkmcnt(0)
	v_add_f32_e32 v114, v114, v115
	ds_bpermute_b32 v115, v162, v114
	s_and_saveexec_b64 s[12:13], s[6:7]
	s_cbranch_execz .LBB0_323
	s_waitcnt lgkmcnt(0)
	v_add_f32_e32 v116, v114, v115
	v_lshlrev_b64 v[114:115], 6, v[154:155]
	v_lshl_add_u64 v[114:115], s[82:83], 0, v[114:115]
	v_lshl_add_u64 v[114:115], vcc, 2, v[114:115]
	s_lshl_b32 s60, s53, 2
	v_lshl_add_u64 v[114:115], v[114:115], 0, s[60:61]
	global_store_dword v[114:115], v116, off
.LBB0_323:
	s_or_b64 exec, exec, s[12:13]
	v_or_b32_e32 v114, 16, v154
	s_waitcnt lgkmcnt(0)
	v_ashrrev_i32_e32 v115, 31, v114
	v_lshlrev_b64 v[116:117], 11, v[114:115]
	v_lshl_add_u64 v[116:117], s[78:79], 0, v[116:117]
	v_lshl_add_u64 v[120:121], v[152:153], 1, v[116:117]
	s_waitcnt vmcnt(16)
	v_lshlrev_b32_e32 v122, 16, v194
	v_and_b32_e32 v123, 0xffff0000, v194
	v_lshlrev_b32_e32 v116, 16, v195
	v_and_b32_e32 v117, 0xffff0000, v195
	v_lshlrev_b32_e32 v124, 16, v196
	v_and_b32_e32 v125, 0xffff0000, v196
	v_lshlrev_b32_e32 v118, 16, v197
	v_and_b32_e32 v119, 0xffff0000, v197
	v_pk_add_f32 v[112:113], v[112:113], v[116:117]
	v_pk_add_f32 v[110:111], v[110:111], v[122:123]
	v_pk_add_f32 v[116:117], v[108:109], v[118:119]
	v_pk_add_f32 v[118:119], v[106:107], v[124:125]
	v_cvt_pk_bf16_f32 v106, v110, v111
	v_cvt_pk_bf16_f32 v107, v112, v113
	v_cvt_pk_bf16_f32 v108, v118, v119
	v_cvt_pk_bf16_f32 v109, v116, v117
	global_store_dwordx4 v[120:121], v[106:109], off
	s_nop 1
	v_mul_f32_e32 v106, v111, v111
	v_mul_f32_e32 v107, v113, v113
	v_fmac_f32_e32 v106, v110, v110
	v_fmac_f32_e32 v107, v112, v112
	v_add_f32_e32 v106, v106, v107
	v_mul_f32_e32 v107, v119, v119
	v_fmac_f32_e32 v107, v118, v118
	v_add_f32_e32 v106, v107, v106
	v_mul_f32_e32 v107, v117, v117
	v_fmac_f32_e32 v107, v116, v116
	v_add_f32_e32 v116, v107, v106
	s_waitcnt vmcnt(16)
	v_lshlrev_b32_e32 v110, 16, v198
	v_and_b32_e32 v111, 0xffff0000, v198
	v_lshlrev_b32_e32 v106, 16, v199
	v_and_b32_e32 v107, 0xffff0000, v199
	v_lshlrev_b32_e32 v112, 16, v200
	v_and_b32_e32 v113, 0xffff0000, v200
	v_lshlrev_b32_e32 v108, 16, v201
	v_and_b32_e32 v109, 0xffff0000, v201
	v_pk_add_f32 v[104:105], v[104:105], v[106:107]
	v_pk_add_f32 v[102:103], v[102:103], v[110:111]
	v_pk_add_f32 v[106:107], v[100:101], v[108:109]
	v_pk_add_f32 v[108:109], v[98:99], v[112:113]
	v_cvt_pk_bf16_f32 v98, v102, v103
	v_cvt_pk_bf16_f32 v99, v104, v105
	v_cvt_pk_bf16_f32 v100, v108, v109
	v_cvt_pk_bf16_f32 v101, v106, v107
	global_store_dwordx4 v[120:121], v[98:101], off offset:256
	s_nop 1
	v_mul_f32_e32 v98, v103, v103
	v_mul_f32_e32 v99, v105, v105
	v_fmac_f32_e32 v98, v102, v102
	v_fmac_f32_e32 v99, v104, v104
	v_add_f32_e32 v98, v98, v99
	v_mul_f32_e32 v99, v109, v109
	v_fmac_f32_e32 v99, v108, v108
	v_add_f32_e32 v98, v99, v98
	v_mul_f32_e32 v99, v107, v107
	v_fmac_f32_e32 v99, v106, v106
	v_add_f32_e32 v98, v99, v98
	v_add_f32_e32 v98, v116, v98
	ds_bpermute_b32 v99, v164, v98
	s_waitcnt lgkmcnt(0)
	v_add_f32_e32 v98, v98, v99
	ds_bpermute_b32 v99, v162, v98
	s_and_saveexec_b64 s[12:13], s[6:7]
	s_cbranch_execz .LBB0_325
	s_waitcnt lgkmcnt(0)
	v_add_f32_e32 v100, v98, v99
	v_lshlrev_b64 v[98:99], 6, v[114:115]
	v_lshl_add_u64 v[98:99], s[82:83], 0, v[98:99]
	v_lshl_add_u64 v[98:99], vcc, 2, v[98:99]
	s_lshl_b32 s60, s53, 2
	v_lshl_add_u64 v[98:99], v[98:99], 0, s[60:61]
	global_store_dword v[98:99], v100, off
.LBB0_325:
	s_or_b64 exec, exec, s[12:13]
	v_or_b32_e32 v98, 32, v154
	s_waitcnt lgkmcnt(0)
	v_ashrrev_i32_e32 v99, 31, v98
	v_lshlrev_b64 v[100:101], 11, v[98:99]
	v_lshl_add_u64 v[100:101], s[78:79], 0, v[100:101]
	v_lshl_add_u64 v[104:105], v[152:153], 1, v[100:101]
	s_waitcnt vmcnt(17)
	v_lshlrev_b32_e32 v106, 16, v202
	v_and_b32_e32 v107, 0xffff0000, v202
	v_lshlrev_b32_e32 v100, 16, v203
	v_and_b32_e32 v101, 0xffff0000, v203
	v_lshlrev_b32_e32 v108, 16, v204
	v_and_b32_e32 v109, 0xffff0000, v204
	v_lshlrev_b32_e32 v102, 16, v205
	v_and_b32_e32 v103, 0xffff0000, v205
	v_pk_add_f32 v[96:97], v[96:97], v[100:101]
	v_pk_add_f32 v[94:95], v[94:95], v[106:107]
	v_pk_add_f32 v[100:101], v[92:93], v[102:103]
	v_pk_add_f32 v[102:103], v[90:91], v[108:109]
	v_cvt_pk_bf16_f32 v90, v94, v95
	v_cvt_pk_bf16_f32 v91, v96, v97
	v_cvt_pk_bf16_f32 v92, v102, v103
	v_cvt_pk_bf16_f32 v93, v100, v101
	global_store_dwordx4 v[104:105], v[90:93], off
	s_nop 1
	v_mul_f32_e32 v90, v95, v95
	v_mul_f32_e32 v91, v97, v97
	v_fmac_f32_e32 v90, v94, v94
	v_fmac_f32_e32 v91, v96, v96
	v_add_f32_e32 v90, v90, v91
	v_mul_f32_e32 v91, v103, v103
	v_fmac_f32_e32 v91, v102, v102
	v_add_f32_e32 v90, v91, v90
	v_mul_f32_e32 v91, v101, v101
	v_fmac_f32_e32 v91, v100, v100
	v_add_f32_e32 v100, v91, v90
	s_waitcnt vmcnt(17)
	v_lshlrev_b32_e32 v94, 16, v206
	v_and_b32_e32 v95, 0xffff0000, v206
	v_lshlrev_b32_e32 v90, 16, v207
	v_and_b32_e32 v91, 0xffff0000, v207
	v_lshlrev_b32_e32 v96, 16, v208
	v_and_b32_e32 v97, 0xffff0000, v208
	v_lshlrev_b32_e32 v92, 16, v209
	v_and_b32_e32 v93, 0xffff0000, v209
	v_pk_add_f32 v[88:89], v[88:89], v[90:91]
	v_pk_add_f32 v[86:87], v[86:87], v[94:95]
	v_pk_add_f32 v[90:91], v[84:85], v[92:93]
	v_pk_add_f32 v[92:93], v[82:83], v[96:97]
	v_cvt_pk_bf16_f32 v82, v86, v87
	v_cvt_pk_bf16_f32 v83, v88, v89
	v_cvt_pk_bf16_f32 v84, v92, v93
	v_cvt_pk_bf16_f32 v85, v90, v91
	global_store_dwordx4 v[104:105], v[82:85], off offset:256
	s_nop 1
	v_mul_f32_e32 v82, v87, v87
	v_mul_f32_e32 v83, v89, v89
	v_fmac_f32_e32 v82, v86, v86
	v_fmac_f32_e32 v83, v88, v88
	v_add_f32_e32 v82, v82, v83
	v_mul_f32_e32 v83, v93, v93
	v_fmac_f32_e32 v83, v92, v92
	v_add_f32_e32 v82, v83, v82
	v_mul_f32_e32 v83, v91, v91
	v_fmac_f32_e32 v83, v90, v90
	v_add_f32_e32 v82, v83, v82
	v_add_f32_e32 v82, v100, v82
	ds_bpermute_b32 v83, v164, v82
	s_waitcnt lgkmcnt(0)
	v_add_f32_e32 v82, v82, v83
	ds_bpermute_b32 v83, v162, v82
	s_and_saveexec_b64 s[12:13], s[6:7]
	s_cbranch_execz .LBB0_327
	s_waitcnt lgkmcnt(0)
	v_add_f32_e32 v84, v82, v83
	v_lshlrev_b64 v[82:83], 6, v[98:99]
	v_lshl_add_u64 v[82:83], s[82:83], 0, v[82:83]
	v_lshl_add_u64 v[82:83], vcc, 2, v[82:83]
	s_lshl_b32 s60, s53, 2
	v_lshl_add_u64 v[82:83], v[82:83], 0, s[60:61]
	global_store_dword v[82:83], v84, off
.LBB0_327:
	s_or_b64 exec, exec, s[12:13]
	v_or_b32_e32 v82, 48, v154
	s_waitcnt lgkmcnt(0)
	v_ashrrev_i32_e32 v83, 31, v82
	v_lshlrev_b64 v[84:85], 11, v[82:83]
	v_lshl_add_u64 v[84:85], s[78:79], 0, v[84:85]
	v_lshl_add_u64 v[88:89], v[152:153], 1, v[84:85]
	s_waitcnt vmcnt(18)
	v_lshlrev_b32_e32 v90, 16, v210
	v_and_b32_e32 v91, 0xffff0000, v210
	v_lshlrev_b32_e32 v84, 16, v211
	v_and_b32_e32 v85, 0xffff0000, v211
	v_lshlrev_b32_e32 v92, 16, v212
	v_and_b32_e32 v93, 0xffff0000, v212
	v_lshlrev_b32_e32 v86, 16, v213
	v_and_b32_e32 v87, 0xffff0000, v213
	v_pk_add_f32 v[80:81], v[80:81], v[84:85]
	v_pk_add_f32 v[78:79], v[78:79], v[90:91]
	v_pk_add_f32 v[84:85], v[76:77], v[86:87]
	v_pk_add_f32 v[86:87], v[74:75], v[92:93]
	v_cvt_pk_bf16_f32 v74, v78, v79
	v_cvt_pk_bf16_f32 v75, v80, v81
	v_cvt_pk_bf16_f32 v76, v86, v87
	v_cvt_pk_bf16_f32 v77, v84, v85
	global_store_dwordx4 v[88:89], v[74:77], off
	s_nop 1
	v_mul_f32_e32 v74, v79, v79
	v_mul_f32_e32 v75, v81, v81
	v_fmac_f32_e32 v74, v78, v78
	v_fmac_f32_e32 v75, v80, v80
	v_add_f32_e32 v74, v74, v75
	v_mul_f32_e32 v75, v87, v87
	v_fmac_f32_e32 v75, v86, v86
	v_add_f32_e32 v74, v75, v74
	v_mul_f32_e32 v75, v85, v85
	v_fmac_f32_e32 v75, v84, v84
	v_add_f32_e32 v84, v75, v74
	s_waitcnt vmcnt(18)
	v_lshlrev_b32_e32 v78, 16, v214
	v_and_b32_e32 v79, 0xffff0000, v214
	v_lshlrev_b32_e32 v74, 16, v215
	v_and_b32_e32 v75, 0xffff0000, v215
	v_lshlrev_b32_e32 v80, 16, v216
	v_and_b32_e32 v81, 0xffff0000, v216
	v_lshlrev_b32_e32 v76, 16, v217
	v_and_b32_e32 v77, 0xffff0000, v217
	v_pk_add_f32 v[72:73], v[72:73], v[74:75]
	v_pk_add_f32 v[70:71], v[70:71], v[78:79]
	v_pk_add_f32 v[74:75], v[68:69], v[76:77]
	v_pk_add_f32 v[76:77], v[66:67], v[80:81]
	v_cvt_pk_bf16_f32 v66, v70, v71
	v_cvt_pk_bf16_f32 v67, v72, v73
	v_cvt_pk_bf16_f32 v68, v76, v77
	v_cvt_pk_bf16_f32 v69, v74, v75
	global_store_dwordx4 v[88:89], v[66:69], off offset:256
	s_nop 1
	v_mul_f32_e32 v66, v71, v71
	v_mul_f32_e32 v67, v73, v73
	v_fmac_f32_e32 v66, v70, v70
	v_fmac_f32_e32 v67, v72, v72
	v_add_f32_e32 v66, v66, v67
	v_mul_f32_e32 v67, v77, v77
	v_fmac_f32_e32 v67, v76, v76
	v_add_f32_e32 v66, v67, v66
	v_mul_f32_e32 v67, v75, v75
	v_fmac_f32_e32 v67, v74, v74
	v_add_f32_e32 v66, v67, v66
	v_add_f32_e32 v66, v84, v66
	ds_bpermute_b32 v67, v164, v66
	s_waitcnt lgkmcnt(0)
	v_add_f32_e32 v66, v66, v67
	ds_bpermute_b32 v67, v162, v66
	s_and_saveexec_b64 s[12:13], s[6:7]
	s_cbranch_execz .LBB0_329
	s_waitcnt lgkmcnt(0)
	v_add_f32_e32 v68, v66, v67
	v_lshlrev_b64 v[66:67], 6, v[82:83]
	v_lshl_add_u64 v[66:67], s[82:83], 0, v[66:67]
	v_lshl_add_u64 v[66:67], vcc, 2, v[66:67]
	s_lshl_b32 s60, s53, 2
	v_lshl_add_u64 v[66:67], v[66:67], 0, s[60:61]
	global_store_dword v[66:67], v68, off
.LBB0_329:
	s_or_b64 exec, exec, s[12:13]
	v_add_u32_e32 v66, 0x80, v154
	s_waitcnt lgkmcnt(0)
	v_ashrrev_i32_e32 v67, 31, v66
	v_lshlrev_b64 v[68:69], 11, v[66:67]
	v_lshl_add_u64 v[68:69], s[78:79], 0, v[68:69]
	v_lshl_add_u64 v[72:73], v[152:153], 1, v[68:69]
	s_waitcnt vmcnt(19)
	v_lshlrev_b32_e32 v74, 16, v218
	v_and_b32_e32 v75, 0xffff0000, v218
	v_lshlrev_b32_e32 v68, 16, v219
	v_and_b32_e32 v69, 0xffff0000, v219
	v_lshlrev_b32_e32 v76, 16, v220
	v_and_b32_e32 v77, 0xffff0000, v220
	v_lshlrev_b32_e32 v70, 16, v221
	v_and_b32_e32 v71, 0xffff0000, v221
	v_pk_add_f32 v[64:65], v[64:65], v[68:69]
	v_pk_add_f32 v[62:63], v[62:63], v[74:75]
	v_pk_add_f32 v[68:69], v[60:61], v[70:71]
	v_pk_add_f32 v[70:71], v[58:59], v[76:77]
	v_cvt_pk_bf16_f32 v58, v62, v63
	v_cvt_pk_bf16_f32 v59, v64, v65
	v_cvt_pk_bf16_f32 v60, v70, v71
	v_cvt_pk_bf16_f32 v61, v68, v69
	global_store_dwordx4 v[72:73], v[58:61], off
	s_nop 1
	v_mul_f32_e32 v58, v63, v63
	v_mul_f32_e32 v59, v65, v65
	v_fmac_f32_e32 v58, v62, v62
	v_fmac_f32_e32 v59, v64, v64
	v_add_f32_e32 v58, v58, v59
	v_mul_f32_e32 v59, v71, v71
	v_fmac_f32_e32 v59, v70, v70
	v_add_f32_e32 v58, v59, v58
	v_mul_f32_e32 v59, v69, v69
	v_fmac_f32_e32 v59, v68, v68
	v_add_f32_e32 v68, v59, v58
	s_waitcnt vmcnt(19)
	v_lshlrev_b32_e32 v62, 16, v222
	v_and_b32_e32 v63, 0xffff0000, v222
	v_lshlrev_b32_e32 v58, 16, v223
	v_and_b32_e32 v59, 0xffff0000, v223
	v_lshlrev_b32_e32 v64, 16, v224
	v_and_b32_e32 v65, 0xffff0000, v224
	v_lshlrev_b32_e32 v60, 16, v225
	v_and_b32_e32 v61, 0xffff0000, v225
	v_pk_add_f32 v[56:57], v[56:57], v[58:59]
	v_pk_add_f32 v[54:55], v[54:55], v[62:63]
	v_pk_add_f32 v[58:59], v[52:53], v[60:61]
	v_pk_add_f32 v[60:61], v[50:51], v[64:65]
	v_cvt_pk_bf16_f32 v50, v54, v55
	v_cvt_pk_bf16_f32 v51, v56, v57
	v_cvt_pk_bf16_f32 v52, v60, v61
	v_cvt_pk_bf16_f32 v53, v58, v59
	global_store_dwordx4 v[72:73], v[50:53], off offset:256
	s_nop 1
	v_mul_f32_e32 v50, v55, v55
	v_mul_f32_e32 v51, v57, v57
	v_fmac_f32_e32 v50, v54, v54
	v_fmac_f32_e32 v51, v56, v56
	v_add_f32_e32 v50, v50, v51
	v_mul_f32_e32 v51, v61, v61
	v_fmac_f32_e32 v51, v60, v60
	v_add_f32_e32 v50, v51, v50
	v_mul_f32_e32 v51, v59, v59
	v_fmac_f32_e32 v51, v58, v58
	v_add_f32_e32 v50, v51, v50
	v_add_f32_e32 v50, v68, v50
	ds_bpermute_b32 v51, v164, v50
	s_waitcnt lgkmcnt(0)
	v_add_f32_e32 v50, v50, v51
	ds_bpermute_b32 v51, v162, v50
	s_and_saveexec_b64 s[12:13], s[6:7]
	s_cbranch_execz .LBB0_331
	s_waitcnt lgkmcnt(0)
	v_add_f32_e32 v52, v50, v51
	v_lshlrev_b64 v[50:51], 6, v[66:67]
	v_lshl_add_u64 v[50:51], s[82:83], 0, v[50:51]
	v_lshl_add_u64 v[50:51], vcc, 2, v[50:51]
	s_lshl_b32 s60, s53, 2
	v_lshl_add_u64 v[50:51], v[50:51], 0, s[60:61]
	global_store_dword v[50:51], v52, off
.LBB0_331:
	s_or_b64 exec, exec, s[12:13]
	v_add_u32_e32 v50, 0x90, v154
	s_waitcnt lgkmcnt(0)
	v_ashrrev_i32_e32 v51, 31, v50
	v_lshlrev_b64 v[52:53], 11, v[50:51]
	v_lshl_add_u64 v[52:53], s[78:79], 0, v[52:53]
	v_lshl_add_u64 v[56:57], v[152:153], 1, v[52:53]
	s_waitcnt vmcnt(20)
	v_lshlrev_b32_e32 v58, 16, v226
	v_and_b32_e32 v59, 0xffff0000, v226
	v_lshlrev_b32_e32 v52, 16, v227
	v_and_b32_e32 v53, 0xffff0000, v227
	v_lshlrev_b32_e32 v60, 16, v228
	v_and_b32_e32 v61, 0xffff0000, v228
	v_lshlrev_b32_e32 v54, 16, v229
	v_and_b32_e32 v55, 0xffff0000, v229
	v_pk_add_f32 v[48:49], v[48:49], v[52:53]
	v_pk_add_f32 v[46:47], v[46:47], v[58:59]
	v_pk_add_f32 v[52:53], v[44:45], v[54:55]
	v_pk_add_f32 v[54:55], v[42:43], v[60:61]
	v_cvt_pk_bf16_f32 v42, v46, v47
	v_cvt_pk_bf16_f32 v43, v48, v49
	v_cvt_pk_bf16_f32 v44, v54, v55
	v_cvt_pk_bf16_f32 v45, v52, v53
	global_store_dwordx4 v[56:57], v[42:45], off
	s_nop 1
	v_mul_f32_e32 v42, v47, v47
	v_mul_f32_e32 v43, v49, v49
	v_fmac_f32_e32 v42, v46, v46
	v_fmac_f32_e32 v43, v48, v48
	v_add_f32_e32 v42, v42, v43
	v_mul_f32_e32 v43, v55, v55
	v_fmac_f32_e32 v43, v54, v54
	v_add_f32_e32 v42, v43, v42
	v_mul_f32_e32 v43, v53, v53
	v_fmac_f32_e32 v43, v52, v52
	v_add_f32_e32 v52, v43, v42
	s_waitcnt vmcnt(20)
	v_lshlrev_b32_e32 v46, 16, v230
	v_and_b32_e32 v47, 0xffff0000, v230
	v_lshlrev_b32_e32 v42, 16, v231
	v_and_b32_e32 v43, 0xffff0000, v231
	v_lshlrev_b32_e32 v48, 16, v232
	v_and_b32_e32 v49, 0xffff0000, v232
	v_lshlrev_b32_e32 v44, 16, v233
	v_and_b32_e32 v45, 0xffff0000, v233
	v_pk_add_f32 v[40:41], v[40:41], v[42:43]
	v_pk_add_f32 v[38:39], v[38:39], v[46:47]
	v_pk_add_f32 v[42:43], v[36:37], v[44:45]
	v_pk_add_f32 v[44:45], v[34:35], v[48:49]
	v_cvt_pk_bf16_f32 v34, v38, v39
	v_cvt_pk_bf16_f32 v35, v40, v41
	v_cvt_pk_bf16_f32 v36, v44, v45
	v_cvt_pk_bf16_f32 v37, v42, v43
	global_store_dwordx4 v[56:57], v[34:37], off offset:256
	s_nop 1
	v_mul_f32_e32 v34, v39, v39
	v_mul_f32_e32 v35, v41, v41
	v_fmac_f32_e32 v34, v38, v38
	v_fmac_f32_e32 v35, v40, v40
	v_add_f32_e32 v34, v34, v35
	v_mul_f32_e32 v35, v45, v45
	v_fmac_f32_e32 v35, v44, v44
	v_add_f32_e32 v34, v35, v34
	v_mul_f32_e32 v35, v43, v43
	v_fmac_f32_e32 v35, v42, v42
	v_add_f32_e32 v34, v35, v34
	v_add_f32_e32 v34, v52, v34
	ds_bpermute_b32 v35, v164, v34
	s_waitcnt lgkmcnt(0)
	v_add_f32_e32 v34, v34, v35
	ds_bpermute_b32 v35, v162, v34
	s_and_saveexec_b64 s[12:13], s[6:7]
	s_cbranch_execz .LBB0_333
	s_waitcnt lgkmcnt(0)
	v_add_f32_e32 v36, v34, v35
	v_lshlrev_b64 v[34:35], 6, v[50:51]
	v_lshl_add_u64 v[34:35], s[82:83], 0, v[34:35]
	v_lshl_add_u64 v[34:35], vcc, 2, v[34:35]
	s_lshl_b32 s60, s53, 2
	v_lshl_add_u64 v[34:35], v[34:35], 0, s[60:61]
	global_store_dword v[34:35], v36, off
.LBB0_333:
	s_or_b64 exec, exec, s[12:13]
	v_add_u32_e32 v34, 0xa0, v154
	s_waitcnt lgkmcnt(0)
	v_ashrrev_i32_e32 v35, 31, v34
	v_lshlrev_b64 v[36:37], 11, v[34:35]
	v_lshl_add_u64 v[36:37], s[78:79], 0, v[36:37]
	v_lshl_add_u64 v[40:41], v[152:153], 1, v[36:37]
	s_waitcnt vmcnt(21)
	v_lshlrev_b32_e32 v42, 16, v234
	v_and_b32_e32 v43, 0xffff0000, v234
	v_lshlrev_b32_e32 v36, 16, v235
	v_and_b32_e32 v37, 0xffff0000, v235
	v_lshlrev_b32_e32 v44, 16, v236
	v_and_b32_e32 v45, 0xffff0000, v236
	v_lshlrev_b32_e32 v38, 16, v237
	v_and_b32_e32 v39, 0xffff0000, v237
	v_pk_add_f32 v[32:33], v[32:33], v[36:37]
	v_pk_add_f32 v[30:31], v[30:31], v[42:43]
	v_pk_add_f32 v[36:37], v[28:29], v[38:39]
	v_pk_add_f32 v[38:39], v[26:27], v[44:45]
	v_cvt_pk_bf16_f32 v26, v30, v31
	v_cvt_pk_bf16_f32 v27, v32, v33
	v_cvt_pk_bf16_f32 v28, v38, v39
	v_cvt_pk_bf16_f32 v29, v36, v37
	global_store_dwordx4 v[40:41], v[26:29], off
	s_nop 1
	v_mul_f32_e32 v26, v31, v31
	v_mul_f32_e32 v27, v33, v33
	v_fmac_f32_e32 v26, v30, v30
	v_fmac_f32_e32 v27, v32, v32
	v_add_f32_e32 v26, v26, v27
	v_mul_f32_e32 v27, v39, v39
	v_fmac_f32_e32 v27, v38, v38
	v_add_f32_e32 v26, v27, v26
	v_mul_f32_e32 v27, v37, v37
	v_fmac_f32_e32 v27, v36, v36
	v_add_f32_e32 v36, v27, v26
	s_waitcnt vmcnt(21)
	v_lshlrev_b32_e32 v30, 16, v238
	v_and_b32_e32 v31, 0xffff0000, v238
	v_lshlrev_b32_e32 v26, 16, v239
	v_and_b32_e32 v27, 0xffff0000, v239
	v_lshlrev_b32_e32 v32, 16, v240
	v_and_b32_e32 v33, 0xffff0000, v240
	v_lshlrev_b32_e32 v28, 16, v241
	v_and_b32_e32 v29, 0xffff0000, v241
	v_pk_add_f32 v[24:25], v[24:25], v[26:27]
	v_pk_add_f32 v[22:23], v[22:23], v[30:31]
	v_pk_add_f32 v[26:27], v[20:21], v[28:29]
	v_pk_add_f32 v[28:29], v[18:19], v[32:33]
	v_cvt_pk_bf16_f32 v18, v22, v23
	v_cvt_pk_bf16_f32 v19, v24, v25
	v_cvt_pk_bf16_f32 v20, v28, v29
	v_cvt_pk_bf16_f32 v21, v26, v27
	global_store_dwordx4 v[40:41], v[18:21], off offset:256
	s_nop 1
	v_mul_f32_e32 v18, v23, v23
	v_mul_f32_e32 v19, v25, v25
	v_fmac_f32_e32 v18, v22, v22
	v_fmac_f32_e32 v19, v24, v24
	v_add_f32_e32 v18, v18, v19
	v_mul_f32_e32 v19, v29, v29
	v_fmac_f32_e32 v19, v28, v28
	v_add_f32_e32 v18, v19, v18
	v_mul_f32_e32 v19, v27, v27
	v_fmac_f32_e32 v19, v26, v26
	v_add_f32_e32 v18, v19, v18
	v_add_f32_e32 v18, v36, v18
	ds_bpermute_b32 v19, v164, v18
	s_waitcnt lgkmcnt(0)
	v_add_f32_e32 v18, v18, v19
	ds_bpermute_b32 v19, v162, v18
	s_and_saveexec_b64 s[12:13], s[6:7]
	s_cbranch_execz .LBB0_335
	s_waitcnt lgkmcnt(0)
	v_add_f32_e32 v20, v18, v19
	v_lshlrev_b64 v[18:19], 6, v[34:35]
	v_lshl_add_u64 v[18:19], s[82:83], 0, v[18:19]
	v_lshl_add_u64 v[18:19], vcc, 2, v[18:19]
	s_lshl_b32 s60, s53, 2
	v_lshl_add_u64 v[18:19], v[18:19], 0, s[60:61]
	global_store_dword v[18:19], v20, off
.LBB0_335:
	s_or_b64 exec, exec, s[12:13]
	v_add_u32_e32 v18, 0xb0, v154
	s_waitcnt lgkmcnt(0)
	v_ashrrev_i32_e32 v19, 31, v18
	v_lshlrev_b64 v[20:21], 11, v[18:19]
	v_lshl_add_u64 v[20:21], s[78:79], 0, v[20:21]
	v_lshl_add_u64 v[24:25], v[152:153], 1, v[20:21]
	s_waitcnt vmcnt(22)
	v_lshlrev_b32_e32 v26, 16, v242
	v_and_b32_e32 v27, 0xffff0000, v242
	v_lshlrev_b32_e32 v20, 16, v243
	v_and_b32_e32 v21, 0xffff0000, v243
	v_lshlrev_b32_e32 v28, 16, v244
	v_and_b32_e32 v29, 0xffff0000, v244
	v_lshlrev_b32_e32 v22, 16, v245
	v_and_b32_e32 v23, 0xffff0000, v245
	v_pk_add_f32 v[16:17], v[16:17], v[20:21]
	v_pk_add_f32 v[14:15], v[14:15], v[26:27]
	v_pk_add_f32 v[20:21], v[12:13], v[22:23]
	v_pk_add_f32 v[22:23], v[10:11], v[28:29]
	v_cvt_pk_bf16_f32 v10, v14, v15
	v_cvt_pk_bf16_f32 v11, v16, v17
	v_cvt_pk_bf16_f32 v12, v22, v23
	v_cvt_pk_bf16_f32 v13, v20, v21
	global_store_dwordx4 v[24:25], v[10:13], off
	s_nop 1
	v_mul_f32_e32 v10, v15, v15
	v_mul_f32_e32 v11, v17, v17
	v_fmac_f32_e32 v10, v14, v14
	v_fmac_f32_e32 v11, v16, v16
	v_add_f32_e32 v10, v10, v11
	v_mul_f32_e32 v11, v23, v23
	v_fmac_f32_e32 v11, v22, v22
	v_add_f32_e32 v10, v11, v10
	v_mul_f32_e32 v11, v21, v21
	v_fmac_f32_e32 v11, v20, v20
	v_add_f32_e32 v20, v11, v10
	s_waitcnt vmcnt(22)
	v_lshlrev_b32_e32 v14, 16, v246
	v_and_b32_e32 v15, 0xffff0000, v246
	v_lshlrev_b32_e32 v10, 16, v247
	v_and_b32_e32 v11, 0xffff0000, v247
	v_lshlrev_b32_e32 v16, 16, v248
	v_and_b32_e32 v17, 0xffff0000, v248
	v_lshlrev_b32_e32 v12, 16, v249
	v_and_b32_e32 v13, 0xffff0000, v249
	v_pk_add_f32 v[8:9], v[8:9], v[10:11]
	v_pk_add_f32 v[6:7], v[6:7], v[14:15]
	v_pk_add_f32 v[10:11], v[4:5], v[12:13]
	v_pk_add_f32 v[12:13], v[2:3], v[16:17]
	v_cvt_pk_bf16_f32 v2, v6, v7
	v_cvt_pk_bf16_f32 v3, v8, v9
	v_cvt_pk_bf16_f32 v4, v12, v13
	v_cvt_pk_bf16_f32 v5, v10, v11
	global_store_dwordx4 v[24:25], v[2:5], off offset:256
	s_nop 1
	v_mul_f32_e32 v2, v7, v7
	v_mul_f32_e32 v3, v9, v9
	v_fmac_f32_e32 v2, v6, v6
	v_fmac_f32_e32 v3, v8, v8
	v_add_f32_e32 v2, v2, v3
	v_mul_f32_e32 v3, v13, v13
	v_fmac_f32_e32 v3, v12, v12
	v_add_f32_e32 v2, v3, v2
	v_mul_f32_e32 v3, v11, v11
	v_fmac_f32_e32 v3, v10, v10
	v_add_f32_e32 v2, v3, v2
	v_add_f32_e32 v2, v20, v2
	ds_bpermute_b32 v3, v164, v2
	s_waitcnt lgkmcnt(0)
	v_add_f32_e32 v2, v2, v3
	ds_bpermute_b32 v3, v162, v2
	s_and_saveexec_b64 s[12:13], s[6:7]
	s_cbranch_execz .LBB0_337
	s_waitcnt lgkmcnt(0)
	v_add_f32_e32 v4, v2, v3
	v_lshlrev_b64 v[2:3], 6, v[18:19]
	v_lshl_add_u64 v[2:3], s[82:83], 0, v[2:3]
	v_lshl_add_u64 v[2:3], vcc, 2, v[2:3]
	s_lshl_b32 s60, s53, 2
	v_lshl_add_u64 v[2:3], v[2:3], 0, s[60:61]
	global_store_dword v[2:3], v4, off
